# no-max attention loop: single lgkmcnt(0) ahead of the K-fragment reads replaces six per-MFMA waits
# speedup vs baseline: 1.0064x; 1.0031x over previous
.LBB0_970:
	v_add_u32_e32 v65, s31, v189
	ds_read_b64_tr_b16 v[178:179], v65 offset:24576
	ds_read_b64_tr_b16 v[180:181], v65 offset:25088
	v_add_f32_e32 v86, v66, v67
	v_add_f32_e32 v86, v68, v86
	v_add_f32_e32 v86, v69, v86
	v_add_f32_e32 v86, v70, v86
	v_add_f32_e32 v86, v71, v86
	v_cvt_pk_bf16_f32 v142, v66, v67
	v_cvt_pk_bf16_f32 v143, v68, v69
	v_mfma_f32_32x32x16_bf16 v[98:113], v[82:85], v[158:161], v[32:47]
	ds_read_b64_tr_b16 v[174:175], v65 offset:28672
	ds_read_b64_tr_b16 v[176:177], v65 offset:29184
	v_add_f32_e32 v66, v72, v86
	v_mfma_f32_32x32x16_bf16 v[82:97], v[166:169], v[158:161], v[32:47]
	v_add_f32_e32 v66, v73, v66
	v_add_f32_e32 v66, v74, v66
	v_add_f32_e32 v130, v75, v66
	v_cvt_pk_bf16_f32 v144, v70, v71
	v_cvt_pk_bf16_f32 v145, v72, v73
	ds_read_b64_tr_b16 v[66:67], v65 offset:25600
	ds_read_b64_tr_b16 v[68:69], v65 offset:26112
	v_add_f32_e32 v70, v76, v130
	v_add_f32_e32 v70, v77, v70
	v_add_f32_e32 v70, v78, v70
	v_add_f32_e32 v130, v79, v70
	v_cvt_pk_bf16_f32 v138, v74, v75
	v_cvt_pk_bf16_f32 v139, v76, v77
	v_mfma_f32_32x32x16_bf16 v[98:113], v[170:173], v[154:157], v[98:113]
	ds_read_b64_tr_b16 v[70:71], v65 offset:29696
	ds_read_b64_tr_b16 v[72:73], v65 offset:30208
	v_mfma_f32_32x32x16_bf16 v[82:97], v[162:165], v[154:157], v[82:97]
	v_add_f32_e32 v74, v80, v130
	v_add_f32_e32 v74, v81, v74
	v_add_f32_e32 v74, v48, v74
	v_add_f32_e32 v130, v49, v74
	v_cvt_pk_bf16_f32 v140, v78, v79
	v_cvt_pk_bf16_f32 v141, v80, v81
	ds_read_b64_tr_b16 v[74:75], v65 offset:26624
	ds_read_b64_tr_b16 v[76:77], v65 offset:27136
	v_add_f32_e32 v78, v50, v130
	v_add_f32_e32 v78, v51, v78
	v_add_f32_e32 v78, v52, v78
	v_add_f32_e32 v78, v53, v78
	v_cvt_pk_bf16_f32 v134, v48, v49
	v_cvt_pk_bf16_f32 v135, v50, v51
	v_mfma_f32_32x32x16_bf16 v[98:113], v[126:129], v[150:153], v[98:113]
	ds_read_b64_tr_b16 v[48:49], v65 offset:30720
	ds_read_b64_tr_b16 v[50:51], v65 offset:31232
	v_mfma_f32_32x32x16_bf16 v[82:97], v[122:125], v[150:153], v[82:97]
	v_add_f32_e32 v78, v54, v78
	v_add_f32_e32 v78, v55, v78
	v_add_f32_e32 v78, v56, v78
	v_add_f32_e32 v78, v57, v78
	v_cvt_pk_bf16_f32 v136, v52, v53
	v_cvt_pk_bf16_f32 v137, v54, v55
	ds_read_b64_tr_b16 v[52:53], v65 offset:27648
	ds_read_b64_tr_b16 v[54:55], v65 offset:28160
	v_add_f32_e32 v78, v58, v78
	v_add_f32_e32 v78, v59, v78
	v_add_f32_e32 v78, v60, v78
	v_add_f32_e32 v78, v61, v78
	v_cvt_pk_bf16_f32 v130, v56, v57
	v_cvt_pk_bf16_f32 v131, v58, v59
	v_mfma_f32_32x32x16_bf16 v[98:113], v[118:121], v[146:149], v[98:113]
	ds_read_b64_tr_b16 v[56:57], v65 offset:31744
	ds_read_b64_tr_b16 v[58:59], v65 offset:32256
	v_mfma_f32_32x32x16_bf16 v[82:97], v[114:117], v[146:149], v[82:97]
	v_add_f32_e32 v65, v62, v78
	v_add_f32_e32 v65, v63, v65
	v_cvt_pk_bf16_f32 v132, v60, v61
	v_cvt_pk_bf16_f32 v133, v62, v63
	v_add_f32_e32 v64, v64, v65
	s_waitcnt lgkmcnt(14)
	v_mfma_f32_32x32x16_bf16 v[0:15], v[142:145], v[178:181], v[0:15]
	s_add_u32 s31, s16, s22
	s_addc_u32 s33, s17, 0
	s_add_i32 m0, s29, s18
	s_add_u32 s34, s31, 0x9ac0800
	s_addc_u32 s35, s33, 0
	global_load_lds_dwordx4 v184, s[34:35]
	v_exp_f32_e32 v98, v98
	v_exp_f32_e32 v99, v99
	v_exp_f32_e32 v100, v100
	v_exp_f32_e32 v101, v101
	s_waitcnt lgkmcnt(12)
	v_mfma_f32_32x32x16_bf16 v[16:31], v[142:145], v[174:177], v[16:31]
	s_add_u32 s34, s20, s22
	s_addc_u32 s35, s21, 0
	s_add_i32 m0, s28, s15
	s_add_u32 s36, s34, 0x9a60a00
	s_addc_u32 s37, s35, 0
	global_load_lds_dwordx4 v185, s[36:37]
	v_exp_f32_e32 v102, v102
	v_exp_f32_e32 v103, v103
	v_exp_f32_e32 v104, v104
	v_exp_f32_e32 v105, v105
	s_waitcnt lgkmcnt(0)
	v_add_u32_e32 v65, s28, v187
	ds_read_b128 v[60:63], v65
	ds_read_b128 v[118:121], v65 offset:512
	v_mfma_f32_32x32x16_bf16 v[0:15], v[138:141], v[66:69], v[0:15]
	v_exp_f32_e32 v106, v106
	v_exp_f32_e32 v107, v107
	v_exp_f32_e32 v108, v108
	v_exp_f32_e32 v109, v109
	ds_read_b128 v[122:125], v65 offset:2048
	ds_read_b128 v[126:129], v65 offset:2560
	v_mfma_f32_32x32x16_bf16 v[16:31], v[138:141], v[70:73], v[16:31]
	v_exp_f32_e32 v110, v110
	v_exp_f32_e32 v111, v111
	v_exp_f32_e32 v112, v112
	v_exp_f32_e32 v113, v113
	ds_read_b128 v[162:165], v65 offset:4096
	ds_read_b128 v[166:169], v65 offset:4608
	v_mfma_f32_32x32x16_bf16 v[0:15], v[134:137], v[74:77], v[0:15]
	v_exp_f32_e32 v82, v82
	v_exp_f32_e32 v83, v83
	v_exp_f32_e32 v84, v84
	v_exp_f32_e32 v85, v85
	ds_read_b128 v[170:173], v65 offset:6144
	ds_read_b128 v[114:117], v65 offset:6656
	v_mfma_f32_32x32x16_bf16 v[16:31], v[134:137], v[48:51], v[16:31]
	v_exp_f32_e32 v86, v86
	v_exp_f32_e32 v87, v87
	v_exp_f32_e32 v88, v88
	v_exp_f32_e32 v89, v89
	v_mfma_f32_32x32x16_bf16 v[0:15], v[130:133], v[52:55], v[0:15]
	v_exp_f32_e32 v90, v90
	v_exp_f32_e32 v91, v91
	v_exp_f32_e32 v92, v92
	v_exp_f32_e32 v93, v93
	v_mfma_f32_32x32x16_bf16 v[16:31], v[130:133], v[56:59], v[16:31]
	v_exp_f32_e32 v94, v94
	v_exp_f32_e32 v95, v95
	v_exp_f32_e32 v96, v96
	v_exp_f32_e32 v97, v97
	s_waitcnt vmcnt(2) lgkmcnt(0)
	s_barrier
	s_add_i32 s30, s28, 0x2000
	s_cmpk_lg_i32 s28, 0x4000
	s_cselect_b32 s30, s30, 0
	v_add_u32_e32 v65, s29, v189
	ds_read_b64_tr_b16 v[174:175], v65 offset:24576
	ds_read_b64_tr_b16 v[176:177], v65 offset:25088
	v_mfma_f32_32x32x16_bf16 v[66:81], v[60:63], v[158:161], v[32:47]
	v_add_f32_e32 v48, v98, v99
	v_add_f32_e32 v48, v100, v48
	v_add_f32_e32 v48, v101, v48
	v_add_f32_e32 v48, v102, v48
	v_add_f32_e32 v48, v103, v48
	v_cvt_pk_bf16_f32 v142, v98, v99
	v_cvt_pk_bf16_f32 v143, v100, v101
	ds_read_b64_tr_b16 v[178:179], v65 offset:28672
	ds_read_b64_tr_b16 v[180:181], v65 offset:29184
	v_add_f32_e32 v48, v104, v48
	v_add_f32_e32 v48, v105, v48
	v_add_f32_e32 v48, v106, v48
	v_add_f32_e32 v130, v107, v48
	v_mfma_f32_32x32x16_bf16 v[48:63], v[118:121], v[158:161], v[32:47]
	v_cvt_pk_bf16_f32 v144, v102, v103
	v_cvt_pk_bf16_f32 v145, v104, v105
	ds_read_b64_tr_b16 v[98:99], v65 offset:25600
	ds_read_b64_tr_b16 v[100:101], v65 offset:26112
	v_mfma_f32_32x32x16_bf16 v[66:81], v[122:125], v[154:157], v[66:81]
	v_add_f32_e32 v102, v108, v130
	v_add_f32_e32 v102, v109, v102
	v_add_f32_e32 v102, v110, v102
	v_add_f32_e32 v118, v111, v102
	v_cvt_pk_bf16_f32 v138, v106, v107
	v_cvt_pk_bf16_f32 v139, v108, v109
	ds_read_b64_tr_b16 v[102:103], v65 offset:29696
	ds_read_b64_tr_b16 v[104:105], v65 offset:30208
	v_mfma_f32_32x32x16_bf16 v[48:63], v[126:129], v[154:157], v[48:63]
	v_add_f32_e32 v106, v112, v118
	v_add_f32_e32 v106, v113, v106
	v_add_f32_e32 v106, v82, v106
	v_add_f32_e32 v118, v83, v106
	v_cvt_pk_bf16_f32 v140, v110, v111
	v_cvt_pk_bf16_f32 v141, v112, v113
	ds_read_b64_tr_b16 v[106:107], v65 offset:26624
	ds_read_b64_tr_b16 v[108:109], v65 offset:27136
	v_mfma_f32_32x32x16_bf16 v[66:81], v[162:165], v[150:153], v[66:81]
	v_add_f32_e32 v110, v84, v118
	v_add_f32_e32 v110, v85, v110
	v_add_f32_e32 v110, v86, v110
	v_add_f32_e32 v118, v87, v110
	v_cvt_pk_bf16_f32 v134, v82, v83
	v_cvt_pk_bf16_f32 v135, v84, v85
	ds_read_b64_tr_b16 v[110:111], v65 offset:30720
	ds_read_b64_tr_b16 v[112:113], v65 offset:31232
	v_mfma_f32_32x32x16_bf16 v[48:63], v[166:169], v[150:153], v[48:63]
	v_add_f32_e32 v82, v88, v118
	v_add_f32_e32 v82, v89, v82
	v_add_f32_e32 v82, v90, v82
	v_add_f32_e32 v82, v91, v82
	v_cvt_pk_bf16_f32 v136, v86, v87
	v_cvt_pk_bf16_f32 v137, v88, v89
	ds_read_b64_tr_b16 v[86:87], v65 offset:27648
	ds_read_b64_tr_b16 v[88:89], v65 offset:28160
	v_mfma_f32_32x32x16_bf16 v[66:81], v[170:173], v[146:149], v[66:81]
	v_add_f32_e32 v82, v92, v82
	v_add_f32_e32 v82, v93, v82
	v_add_f32_e32 v82, v94, v82
	v_add_f32_e32 v82, v95, v82
	v_cvt_pk_bf16_f32 v130, v90, v91
	v_cvt_pk_bf16_f32 v131, v92, v93
	ds_read_b64_tr_b16 v[90:91], v65 offset:31744
	ds_read_b64_tr_b16 v[92:93], v65 offset:32256
	v_mfma_f32_32x32x16_bf16 v[48:63], v[114:117], v[146:149], v[48:63]
	v_add_f32_e32 v65, v96, v82
	v_add_f32_e32 v65, v97, v65
	v_cvt_pk_bf16_f32 v132, v94, v95
	v_cvt_pk_bf16_f32 v133, v96, v97
	v_add_f32_e32 v64, v64, v65
	s_waitcnt lgkmcnt(14)
	v_mfma_f32_32x32x16_bf16 v[0:15], v[142:145], v[174:177], v[0:15]
	s_add_i32 m0, s28, s18
	s_add_u32 s36, s31, 0x9af0800
	s_addc_u32 s37, s33, 0
	global_load_lds_dwordx4 v184, s[36:37]
	v_exp_f32_e32 v66, v66
	v_exp_f32_e32 v67, v67
	v_exp_f32_e32 v68, v68
	v_exp_f32_e32 v69, v69
	s_waitcnt lgkmcnt(12)
	v_mfma_f32_32x32x16_bf16 v[16:31], v[142:145], v[178:181], v[16:31]
	s_add_i32 m0, s30, s15
	s_add_u32 s34, s34, 0x9a90a00
	s_addc_u32 s35, s35, 0
	global_load_lds_dwordx4 v185, s[34:35]
	v_exp_f32_e32 v70, v70
	v_exp_f32_e32 v71, v71
	v_exp_f32_e32 v72, v72
	v_exp_f32_e32 v73, v73
	v_add_u32_e32 v65, s30, v187
	ds_read_b128 v[82:85], v65
	ds_read_b128 v[166:169], v65 offset:512
	v_mfma_f32_32x32x16_bf16 v[0:15], v[138:141], v[98:101], v[0:15]
	v_exp_f32_e32 v74, v74
	s_waitcnt lgkmcnt(0)
	v_exp_f32_e32 v75, v75
	v_exp_f32_e32 v76, v76
	v_exp_f32_e32 v77, v77
	ds_read_b128 v[170:173], v65 offset:2048
	ds_read_b128 v[162:165], v65 offset:2560
	v_mfma_f32_32x32x16_bf16 v[16:31], v[138:141], v[102:105], v[16:31]
	v_exp_f32_e32 v78, v78
	v_exp_f32_e32 v79, v79
	v_exp_f32_e32 v80, v80
	v_exp_f32_e32 v81, v81
	ds_read_b128 v[126:129], v65 offset:4096
	ds_read_b128 v[122:125], v65 offset:4608
	v_mfma_f32_32x32x16_bf16 v[0:15], v[134:137], v[106:109], v[0:15]
	v_exp_f32_e32 v48, v48
	v_exp_f32_e32 v49, v49
	v_exp_f32_e32 v50, v50
	v_exp_f32_e32 v51, v51
	ds_read_b128 v[118:121], v65 offset:6144
	ds_read_b128 v[114:117], v65 offset:6656
	v_mfma_f32_32x32x16_bf16 v[16:31], v[134:137], v[110:113], v[16:31]
	v_exp_f32_e32 v52, v52
	v_exp_f32_e32 v53, v53
	v_exp_f32_e32 v54, v54
	v_exp_f32_e32 v55, v55
	v_mfma_f32_32x32x16_bf16 v[0:15], v[130:133], v[86:89], v[0:15]
	v_exp_f32_e32 v56, v56
	v_exp_f32_e32 v57, v57
	v_exp_f32_e32 v58, v58
	v_exp_f32_e32 v59, v59
	v_mfma_f32_32x32x16_bf16 v[16:31], v[130:133], v[90:93], v[16:31]
	v_exp_f32_e32 v60, v60
	v_exp_f32_e32 v61, v61
	v_exp_f32_e32 v62, v62
	v_exp_f32_e32 v63, v63
	s_add_i32 s33, s30, 0x2000
	s_cmpk_lg_i32 s30, 0x4000
	s_mov_b32 s31, s28
	s_cselect_b32 s28, s33, 0
	s_add_i32 s24, s24, 2
	s_add_u32 s20, s20, 0x60000
	s_addc_u32 s21, s21, 0
	s_waitcnt vmcnt(2) lgkmcnt(0)
	s_barrier
	s_add_u32 s16, s16, 0x60000
	s_addc_u32 s17, s17, 0
	s_mov_b32 s29, s30
	s_cmp_gt_u32 s24, 56
	s_cbranch_scc0 .LBB0_970
	s_and_b32 s16, s23, 0x3fffffc0
	s_lshl_b32 s16, s16, 2
	s_add_i32 s16, s16, 0
	ds_read_b64_tr_b16 v[174:175], v189 offset:32768
	ds_read_b64_tr_b16 v[176:177], v189 offset:33280
	v_add_f32_e32 v65, v66, v67
	v_add_f32_e32 v65, v68, v65
	v_add_f32_e32 v65, v69, v65
	v_add_f32_e32 v65, v70, v65
	v_add_f32_e32 v65, v71, v65
	v_cvt_pk_bf16_f32 v142, v66, v67
	v_cvt_pk_bf16_f32 v143, v68, v69
	s_waitcnt lgkmcnt(9)
	v_mfma_f32_32x32x16_bf16 v[98:113], v[82:85], v[158:161], v[32:47]
	ds_read_b64_tr_b16 v[178:179], v189 offset:36864
	ds_read_b64_tr_b16 v[180:181], v189 offset:37376
	v_add_f32_e32 v65, v72, v65
	v_add_f32_e32 v65, v73, v65
	v_add_f32_e32 v65, v74, v65
	v_add_f32_e32 v65, v75, v65
	v_cvt_pk_bf16_f32 v144, v70, v71
	v_cvt_pk_bf16_f32 v145, v72, v73
	s_waitcnt lgkmcnt(10)
	v_mfma_f32_32x32x16_bf16 v[82:97], v[166:169], v[158:161], v[32:47]
	ds_read_b64_tr_b16 v[66:67], v189 offset:33792
	ds_read_b64_tr_b16 v[68:69], v189 offset:34304
	v_add_f32_e32 v65, v76, v65
	v_add_f32_e32 v65, v77, v65
	v_add_f32_e32 v65, v78, v65
	v_add_f32_e32 v65, v79, v65
	v_cvt_pk_bf16_f32 v138, v74, v75
	v_cvt_pk_bf16_f32 v139, v76, v77
	s_waitcnt lgkmcnt(11)
	v_mfma_f32_32x32x16_bf16 v[98:113], v[170:173], v[154:157], v[98:113]
	ds_read_b64_tr_b16 v[70:71], v189 offset:37888
	ds_read_b64_tr_b16 v[72:73], v189 offset:38400
	v_add_f32_e32 v65, v80, v65
	v_add_f32_e32 v65, v81, v65
	v_add_f32_e32 v65, v48, v65
	v_add_f32_e32 v65, v49, v65
	v_cvt_pk_bf16_f32 v140, v78, v79
	v_cvt_pk_bf16_f32 v141, v80, v81
	s_waitcnt lgkmcnt(12)
	v_mfma_f32_32x32x16_bf16 v[82:97], v[162:165], v[154:157], v[82:97]
	ds_read_b64_tr_b16 v[74:75], v189 offset:34816
	ds_read_b64_tr_b16 v[76:77], v189 offset:35328
	v_add_f32_e32 v65, v50, v65
	v_add_f32_e32 v65, v51, v65
	v_add_f32_e32 v65, v52, v65
	v_add_f32_e32 v65, v53, v65
	v_cvt_pk_bf16_f32 v134, v48, v49
	v_cvt_pk_bf16_f32 v135, v50, v51
	s_waitcnt lgkmcnt(13)
	v_mfma_f32_32x32x16_bf16 v[98:113], v[126:129], v[150:153], v[98:113]
	ds_read_b64_tr_b16 v[48:49], v189 offset:38912
	ds_read_b64_tr_b16 v[50:51], v189 offset:39424
	v_add_f32_e32 v65, v54, v65
	v_add_f32_e32 v65, v55, v65
	v_add_f32_e32 v65, v56, v65
	v_add_f32_e32 v65, v57, v65
	v_cvt_pk_bf16_f32 v136, v52, v53
	v_cvt_pk_bf16_f32 v137, v54, v55
	s_waitcnt lgkmcnt(14)
	v_mfma_f32_32x32x16_bf16 v[82:97], v[122:125], v[150:153], v[82:97]
	ds_read_b64_tr_b16 v[52:53], v189 offset:35840
	ds_read_b64_tr_b16 v[54:55], v189 offset:36352
	v_add_f32_e32 v65, v58, v65
	v_add_f32_e32 v65, v59, v65
	v_add_f32_e32 v65, v60, v65
	v_add_f32_e32 v65, v61, v65
	v_cvt_pk_bf16_f32 v130, v56, v57
	v_cvt_pk_bf16_f32 v131, v58, v59
	s_waitcnt lgkmcnt(14)
	v_mfma_f32_32x32x16_bf16 v[98:113], v[118:121], v[146:149], v[98:113]
	ds_read_b64_tr_b16 v[56:57], v189 offset:39936
	ds_read_b64_tr_b16 v[58:59], v189 offset:40448
	v_add_f32_e32 v65, v62, v65
	v_add_f32_e32 v65, v63, v65
	v_add_f32_e32 v65, 0, v65
	v_cvt_pk_bf16_f32 v132, v60, v61
	v_cvt_pk_bf16_f32 v133, v62, v63
	v_mfma_f32_32x32x16_bf16 v[82:97], v[114:117], v[146:149], v[82:97]
	s_add_u32 s20, s10, 0xba0000
	s_addc_u32 s21, s11, 0
	s_cmp_lg_u32 0, -1
	s_cselect_b32 s17, 0, 0
	s_add_i32 s17, s17, s19
	s_add_i32 s19, s17, 0x4000
	s_mov_b32 s22, m0
	s_mov_b32 m0, s19
	s_nop 0
	global_load_lds_dwordx4 v184, s[20:21]
	s_mov_b32 m0, s22
	s_add_u32 s20, s8, 0xb40000
	s_addc_u32 s21, s9, 0
	s_mov_b32 s19, m0
	s_mov_b32 m0, s15
	s_nop 0
	global_load_lds_dwordx4 v185, s[20:21]
	s_mov_b32 m0, s19
	v_add_f32_e32 v183, v64, v65
	s_waitcnt lgkmcnt(14)
	v_mfma_f32_32x32x16_bf16 v[0:15], v[142:145], v[174:177], v[0:15]
	v_exp_f32_e32 v98, v98
	v_exp_f32_e32 v99, v99
	v_exp_f32_e32 v100, v100
	v_exp_f32_e32 v101, v101
	s_waitcnt lgkmcnt(12)
	v_mfma_f32_32x32x16_bf16 v[16:31], v[142:145], v[178:181], v[16:31]
	v_exp_f32_e32 v102, v102
	v_exp_f32_e32 v103, v103
	v_exp_f32_e32 v104, v104
	v_exp_f32_e32 v105, v105
	ds_read_b128 v[60:63], v187
	ds_read_b128 v[78:81], v187 offset:512
	s_waitcnt lgkmcnt(12)
	v_mfma_f32_32x32x16_bf16 v[0:15], v[138:141], v[66:69], v[0:15]
	v_exp_f32_e32 v106, v106
	v_exp_f32_e32 v107, v107
	v_exp_f32_e32 v108, v108
	v_exp_f32_e32 v109, v109
	ds_read_b128 v[162:165], v187 offset:2048
	ds_read_b128 v[166:169], v187 offset:2560
	s_waitcnt lgkmcnt(12)
	v_mfma_f32_32x32x16_bf16 v[16:31], v[138:141], v[70:73], v[16:31]
	v_exp_f32_e32 v110, v110
	v_exp_f32_e32 v111, v111
	v_exp_f32_e32 v112, v112
	v_exp_f32_e32 v113, v113
	ds_read_b128 v[68:71], v187 offset:4096
	ds_read_b128 v[170:173], v187 offset:4608
	s_waitcnt lgkmcnt(12)
	v_mfma_f32_32x32x16_bf16 v[0:15], v[134:137], v[74:77], v[0:15]
	v_exp_f32_e32 v82, v82
	v_exp_f32_e32 v83, v83
	v_exp_f32_e32 v84, v84
	v_exp_f32_e32 v85, v85
	ds_read_b128 v[72:75], v187 offset:6144
	ds_read_b128 v[64:67], v187 offset:6656
	s_waitcnt lgkmcnt(12)
	v_mfma_f32_32x32x16_bf16 v[16:31], v[134:137], v[48:51], v[16:31]
	v_exp_f32_e32 v86, v86
	v_exp_f32_e32 v87, v87
	v_exp_f32_e32 v88, v88
	v_exp_f32_e32 v89, v89
	s_waitcnt lgkmcnt(10)
	v_mfma_f32_32x32x16_bf16 v[0:15], v[130:133], v[52:55], v[0:15]
	v_exp_f32_e32 v90, v90
	v_exp_f32_e32 v91, v91
	v_exp_f32_e32 v92, v92
	v_exp_f32_e32 v93, v93
	s_waitcnt lgkmcnt(8)
	v_mfma_f32_32x32x16_bf16 v[16:31], v[130:133], v[56:59], v[16:31]
	v_exp_f32_e32 v94, v94
	v_exp_f32_e32 v95, v95
	v_exp_f32_e32 v96, v96
	v_exp_f32_e32 v97, v97
	s_waitcnt vmcnt(2) lgkmcnt(0)
	s_barrier
	ds_read_b64_tr_b16 v[174:175], v189 offset:40960
	ds_read_b64_tr_b16 v[176:177], v189 offset:41472
	v_add_f32_e32 v48, v98, v99
	v_add_f32_e32 v48, v100, v48
	v_add_f32_e32 v48, v101, v48
	v_add_f32_e32 v48, v102, v48
	v_add_f32_e32 v48, v103, v48
	v_cvt_pk_bf16_f32 v142, v98, v99
	v_cvt_pk_bf16_f32 v143, v100, v101
	s_waitcnt lgkmcnt(9)
	v_mfma_f32_32x32x16_bf16 v[114:129], v[60:63], v[158:161], v[32:47]
	ds_read_b64_tr_b16 v[98:99], v189 offset:45056
	ds_read_b64_tr_b16 v[100:101], v189 offset:45568
	v_add_f32_e32 v48, v104, v48
	v_add_f32_e32 v48, v105, v48
	v_add_f32_e32 v48, v106, v48
	v_add_f32_e32 v130, v107, v48
	s_waitcnt lgkmcnt(10)
	v_mfma_f32_32x32x16_bf16 v[48:63], v[78:81], v[158:161], v[32:47]
	v_cvt_pk_bf16_f32 v144, v102, v103
	v_cvt_pk_bf16_f32 v145, v104, v105
	ds_read_b64_tr_b16 v[76:77], v189 offset:41984
	ds_read_b64_tr_b16 v[78:79], v189 offset:42496
	v_add_f32_e32 v80, v108, v130
	v_add_f32_e32 v80, v109, v80
	v_add_f32_e32 v80, v110, v80
	v_add_f32_e32 v80, v111, v80
	v_cvt_pk_bf16_f32 v138, v106, v107
	v_cvt_pk_bf16_f32 v139, v108, v109
	s_waitcnt lgkmcnt(11)
	v_mfma_f32_32x32x16_bf16 v[114:129], v[162:165], v[154:157], v[114:129]
	ds_read_b64_tr_b16 v[102:103], v189 offset:46080
	ds_read_b64_tr_b16 v[104:105], v189 offset:46592
	s_waitcnt lgkmcnt(12)
	v_mfma_f32_32x32x16_bf16 v[48:63], v[166:169], v[154:157], v[48:63]
	v_add_f32_e32 v80, v112, v80
	v_add_f32_e32 v80, v113, v80
	v_add_f32_e32 v80, v82, v80
	v_add_f32_e32 v80, v83, v80
	v_cvt_pk_bf16_f32 v140, v110, v111
	v_cvt_pk_bf16_f32 v141, v112, v113
	ds_read_b64_tr_b16 v[106:107], v189 offset:43008
	ds_read_b64_tr_b16 v[108:109], v189 offset:43520
	s_waitcnt lgkmcnt(13)
	v_mfma_f32_32x32x16_bf16 v[114:129], v[68:71], v[150:153], v[114:129]
	v_add_f32_e32 v68, v84, v80
	v_add_f32_e32 v68, v85, v68
	v_add_f32_e32 v68, v86, v68
	v_add_f32_e32 v80, v87, v68
	v_cvt_pk_bf16_f32 v134, v82, v83
	v_cvt_pk_bf16_f32 v135, v84, v85
	ds_read_b64_tr_b16 v[68:69], v189 offset:47104
	ds_read_b64_tr_b16 v[70:71], v189 offset:47616
	s_waitcnt lgkmcnt(14)
	v_mfma_f32_32x32x16_bf16 v[48:63], v[170:173], v[150:153], v[48:63]
	v_add_f32_e32 v80, v88, v80
	v_add_f32_e32 v80, v89, v80
	v_add_f32_e32 v80, v90, v80
	v_add_f32_e32 v80, v91, v80
	v_cvt_pk_bf16_f32 v136, v86, v87
	v_cvt_pk_bf16_f32 v137, v88, v89
	ds_read_b64_tr_b16 v[84:85], v189 offset:44032
	ds_read_b64_tr_b16 v[86:87], v189 offset:44544
	s_waitcnt lgkmcnt(14)
	v_mfma_f32_32x32x16_bf16 v[114:129], v[72:75], v[146:149], v[114:129]
	v_add_f32_e32 v72, v92, v80
	v_add_f32_e32 v72, v93, v72
	v_add_f32_e32 v72, v94, v72
	v_add_f32_e32 v80, v95, v72
	v_cvt_pk_bf16_f32 v130, v90, v91
	v_cvt_pk_bf16_f32 v131, v92, v93
	ds_read_b64_tr_b16 v[72:73], v189 offset:48128
	ds_read_b64_tr_b16 v[74:75], v189 offset:48640
	v_mfma_f32_32x32x16_bf16 v[48:63], v[64:67], v[146:149], v[48:63]
	v_add_f32_e32 v64, v96, v80
	v_add_f32_e32 v64, v97, v64
	v_add_f32_e32 v64, 0, v64
	v_cvt_pk_bf16_f32 v132, v94, v95
	v_cvt_pk_bf16_f32 v133, v96, v97
	s_add_u32 s10, s10, 0xbd0000
	s_addc_u32 s11, s11, 0
	s_mov_b32 s19, m0
	s_mov_b32 m0, s18
	s_nop 0
	global_load_lds_dwordx4 v184, s[10:11]
	s_mov_b32 m0, s19
	s_add_u32 s10, s8, 0xb70000
	s_addc_u32 s11, s9, 0
	s_add_i32 s18, s17, 0x8000
	s_mov_b32 s19, m0
	s_mov_b32 m0, s18
	s_nop 0
	global_load_lds_dwordx4 v185, s[10:11]
	s_mov_b32 m0, s19
	v_add_f32_e32 v178, v183, v64
	s_waitcnt lgkmcnt(14)
	v_mfma_f32_32x32x16_bf16 v[0:15], v[142:145], v[174:177], v[0:15]
	v_exp_f32_e32 v114, v114
	v_exp_f32_e32 v115, v115
	v_exp_f32_e32 v116, v116
	v_exp_f32_e32 v117, v117
	s_waitcnt lgkmcnt(12)
	v_mfma_f32_32x32x16_bf16 v[16:31], v[142:145], v[98:101], v[16:31]
	v_exp_f32_e32 v118, v118
	v_exp_f32_e32 v119, v119
	v_exp_f32_e32 v120, v120
	v_exp_f32_e32 v121, v121
	ds_read_b128 v[64:67], v187 offset:8192
	ds_read_b128 v[88:91], v187 offset:8704
	s_waitcnt lgkmcnt(12)
	v_mfma_f32_32x32x16_bf16 v[0:15], v[138:141], v[76:79], v[0:15]
	v_exp_f32_e32 v122, v122
	v_exp_f32_e32 v123, v123
	v_exp_f32_e32 v124, v124
	v_exp_f32_e32 v125, v125
	ds_read_b128 v[92:95], v187 offset:10240
	ds_read_b128 v[162:165], v187 offset:10752
	s_waitcnt lgkmcnt(12)
	v_mfma_f32_32x32x16_bf16 v[16:31], v[138:141], v[102:105], v[16:31]
	v_exp_f32_e32 v126, v126
	v_exp_f32_e32 v127, v127
	v_exp_f32_e32 v128, v128
	v_exp_f32_e32 v129, v129
	ds_read_b128 v[166:169], v187 offset:12288
	ds_read_b128 v[170:173], v187 offset:12800
	s_waitcnt lgkmcnt(12)
	v_mfma_f32_32x32x16_bf16 v[0:15], v[134:137], v[106:109], v[0:15]
	v_exp_f32_e32 v48, v48
	v_exp_f32_e32 v49, v49
	v_exp_f32_e32 v50, v50
	v_exp_f32_e32 v51, v51
	ds_read_b128 v[174:177], v187 offset:14336
	ds_read_b128 v[80:83], v187 offset:14848
	s_waitcnt lgkmcnt(12)
	v_mfma_f32_32x32x16_bf16 v[16:31], v[134:137], v[68:71], v[16:31]
	v_exp_f32_e32 v52, v52
	v_exp_f32_e32 v53, v53
	v_exp_f32_e32 v54, v54
	v_exp_f32_e32 v55, v55
	s_waitcnt lgkmcnt(10)
	v_mfma_f32_32x32x16_bf16 v[0:15], v[130:133], v[84:87], v[0:15]
	v_exp_f32_e32 v56, v56
	v_exp_f32_e32 v57, v57
	v_exp_f32_e32 v58, v58
	v_exp_f32_e32 v59, v59
	s_waitcnt lgkmcnt(8)
	v_mfma_f32_32x32x16_bf16 v[16:31], v[130:133], v[72:75], v[16:31]
	v_exp_f32_e32 v60, v60
	v_exp_f32_e32 v61, v61
	v_exp_f32_e32 v62, v62
	v_exp_f32_e32 v63, v63
	s_waitcnt vmcnt(2) lgkmcnt(0)
	s_barrier
	ds_read_b64_tr_b16 v[84:85], v189 offset:24576
	ds_read_b64_tr_b16 v[86:87], v189 offset:25088
	v_add_f32_e32 v68, v114, v115
	v_add_f32_e32 v68, v116, v68
	v_add_f32_e32 v68, v117, v68
	v_add_f32_e32 v68, v118, v68
	v_add_f32_e32 v68, v119, v68
	v_cvt_pk_bf16_f32 v142, v114, v115
	v_cvt_pk_bf16_f32 v143, v116, v117
	s_waitcnt lgkmcnt(9)
	v_mfma_f32_32x32x16_bf16 v[96:111], v[64:67], v[158:161], v[32:47]
	ds_read_b64_tr_b16 v[112:113], v189 offset:28672
	ds_read_b64_tr_b16 v[114:115], v189 offset:29184
	v_add_f32_e32 v64, v120, v68
	v_add_f32_e32 v64, v121, v64
	v_add_f32_e32 v64, v122, v64
	v_add_f32_e32 v116, v123, v64
	v_cvt_pk_bf16_f32 v144, v118, v119
	v_cvt_pk_bf16_f32 v145, v120, v121
	s_waitcnt lgkmcnt(10)
	v_mfma_f32_32x32x16_bf16 v[64:79], v[88:91], v[158:161], v[32:47]
	ds_read_b64_tr_b16 v[88:89], v189 offset:25600
	ds_read_b64_tr_b16 v[90:91], v189 offset:26112
	s_waitcnt lgkmcnt(11)
	v_mfma_f32_32x32x16_bf16 v[96:111], v[92:95], v[154:157], v[96:111]
	v_add_f32_e32 v92, v124, v116
	v_add_f32_e32 v92, v125, v92
	v_add_f32_e32 v92, v126, v92
	v_add_f32_e32 v116, v127, v92
	v_cvt_pk_bf16_f32 v138, v122, v123
	v_cvt_pk_bf16_f32 v139, v124, v125
	ds_read_b64_tr_b16 v[92:93], v189 offset:29696
	ds_read_b64_tr_b16 v[94:95], v189 offset:30208
	v_add_f32_e32 v116, v128, v116
	v_add_f32_e32 v116, v129, v116
	v_add_f32_e32 v116, v48, v116
	v_add_f32_e32 v120, v49, v116
	v_cvt_pk_bf16_f32 v140, v126, v127
	v_cvt_pk_bf16_f32 v141, v128, v129
	s_waitcnt lgkmcnt(12)
	v_mfma_f32_32x32x16_bf16 v[64:79], v[162:165], v[154:157], v[64:79]
	ds_read_b64_tr_b16 v[116:117], v189 offset:26624
	ds_read_b64_tr_b16 v[118:119], v189 offset:27136
	v_add_f32_e32 v120, v50, v120
	v_add_f32_e32 v120, v51, v120
	v_add_f32_e32 v120, v52, v120
	v_add_f32_e32 v120, v53, v120
	v_cvt_pk_bf16_f32 v134, v48, v49
	v_cvt_pk_bf16_f32 v135, v50, v51
	s_waitcnt lgkmcnt(13)
	v_mfma_f32_32x32x16_bf16 v[96:111], v[166:169], v[150:153], v[96:111]
	ds_read_b64_tr_b16 v[48:49], v189 offset:30720
	ds_read_b64_tr_b16 v[50:51], v189 offset:31232
	v_add_f32_e32 v120, v54, v120
	v_add_f32_e32 v120, v55, v120
	v_add_f32_e32 v120, v56, v120
	v_add_f32_e32 v120, v57, v120
	v_cvt_pk_bf16_f32 v136, v52, v53
	v_cvt_pk_bf16_f32 v137, v54, v55
	s_waitcnt lgkmcnt(14)
	v_mfma_f32_32x32x16_bf16 v[64:79], v[170:173], v[150:153], v[64:79]
	ds_read_b64_tr_b16 v[52:53], v189 offset:27648
	ds_read_b64_tr_b16 v[54:55], v189 offset:28160
	v_add_f32_e32 v120, v58, v120
	v_add_f32_e32 v120, v59, v120
	v_add_f32_e32 v120, v60, v120
	v_add_f32_e32 v120, v61, v120
	v_cvt_pk_bf16_f32 v130, v56, v57
	v_cvt_pk_bf16_f32 v131, v58, v59
	s_waitcnt lgkmcnt(14)
	v_mfma_f32_32x32x16_bf16 v[96:111], v[174:177], v[146:149], v[96:111]
	ds_read_b64_tr_b16 v[56:57], v189 offset:31744
	ds_read_b64_tr_b16 v[58:59], v189 offset:32256
	v_mfma_f32_32x32x16_bf16 v[64:79], v[80:83], v[146:149], v[64:79]
	v_add_f32_e32 v80, v62, v120
	v_add_f32_e32 v80, v63, v80
	v_add_f32_e32 v80, 0, v80
	v_cvt_pk_bf16_f32 v132, v60, v61
	v_cvt_pk_bf16_f32 v133, v62, v63
	s_add_u32 s10, s8, 0xba0000
	s_addc_u32 s11, s9, 0
	s_add_i32 s17, s17, 0xa000
	s_mov_b32 s18, m0
	s_mov_b32 m0, s17
	s_nop 0
	global_load_lds_dwordx4 v185, s[10:11]
	s_mov_b32 m0, s18
	v_add_f32_e32 v128, v178, v80
	s_waitcnt lgkmcnt(14)
	v_mfma_f32_32x32x16_bf16 v[0:15], v[142:145], v[84:87], v[0:15]
	v_exp_f32_e32 v96, v96
	v_exp_f32_e32 v97, v97
	v_exp_f32_e32 v98, v98
	v_exp_f32_e32 v99, v99
	s_waitcnt lgkmcnt(12)
	v_mfma_f32_32x32x16_bf16 v[16:31], v[142:145], v[112:115], v[16:31]
	v_exp_f32_e32 v100, v100
	v_exp_f32_e32 v101, v101
	v_exp_f32_e32 v102, v102
	v_exp_f32_e32 v103, v103
	ds_read_b128 v[60:63], v187 offset:16384
	ds_read_b128 v[120:123], v187 offset:16896
	s_waitcnt lgkmcnt(12)
	v_mfma_f32_32x32x16_bf16 v[0:15], v[138:141], v[88:91], v[0:15]
	v_exp_f32_e32 v104, v104
	v_exp_f32_e32 v105, v105
	v_exp_f32_e32 v106, v106
	v_exp_f32_e32 v107, v107
	ds_read_b128 v[124:127], v187 offset:18432
	ds_read_b128 v[162:165], v187 offset:18944
	s_waitcnt lgkmcnt(12)
	v_mfma_f32_32x32x16_bf16 v[16:31], v[138:141], v[92:95], v[16:31]
	v_exp_f32_e32 v108, v108
	v_exp_f32_e32 v109, v109
	v_exp_f32_e32 v110, v110
	v_exp_f32_e32 v111, v111
	ds_read_b128 v[166:169], v187 offset:20480
	ds_read_b128 v[170:173], v187 offset:20992
	s_waitcnt lgkmcnt(12)
	v_mfma_f32_32x32x16_bf16 v[0:15], v[134:137], v[116:119], v[0:15]
	v_exp_f32_e32 v64, v64
	v_exp_f32_e32 v65, v65
	v_exp_f32_e32 v66, v66
	v_exp_f32_e32 v67, v67
	ds_read_b128 v[116:119], v187 offset:22528
	ds_read_b128 v[112:115], v187 offset:23040
	s_waitcnt lgkmcnt(12)
	v_mfma_f32_32x32x16_bf16 v[16:31], v[134:137], v[48:51], v[16:31]
	v_exp_f32_e32 v68, v68
	v_exp_f32_e32 v69, v69
	v_exp_f32_e32 v70, v70
	v_exp_f32_e32 v71, v71
	s_waitcnt lgkmcnt(10)
	v_mfma_f32_32x32x16_bf16 v[0:15], v[130:133], v[52:55], v[0:15]
	v_exp_f32_e32 v72, v72
	v_exp_f32_e32 v73, v73
	v_exp_f32_e32 v74, v74
	v_exp_f32_e32 v75, v75
	s_waitcnt lgkmcnt(8)
	v_mfma_f32_32x32x16_bf16 v[16:31], v[130:133], v[56:59], v[16:31]
	v_exp_f32_e32 v76, v76
	v_exp_f32_e32 v77, v77
	v_exp_f32_e32 v78, v78
	v_exp_f32_e32 v79, v79
	s_waitcnt vmcnt(1) lgkmcnt(0)
	s_barrier
	ds_read_b64_tr_b16 v[174:175], v189 offset:32768
	ds_read_b64_tr_b16 v[176:177], v189 offset:33280
	v_add_f32_e32 v48, v96, v97
	v_add_f32_e32 v48, v98, v48
	v_add_f32_e32 v48, v99, v48
	v_add_f32_e32 v48, v100, v48
	v_add_f32_e32 v48, v101, v48
	v_cvt_pk_bf16_f32 v142, v96, v97
	v_cvt_pk_bf16_f32 v143, v98, v99
	s_waitcnt lgkmcnt(9)
	v_mfma_f32_32x32x16_bf16 v[80:95], v[60:63], v[158:161], v[32:47]
	ds_read_b64_tr_b16 v[96:97], v189 offset:36864
	ds_read_b64_tr_b16 v[98:99], v189 offset:37376
	v_add_f32_e32 v48, v102, v48
	v_add_f32_e32 v48, v103, v48
	v_add_f32_e32 v48, v104, v48
	v_add_f32_e32 v129, v105, v48
	s_waitcnt lgkmcnt(10)
	v_mfma_f32_32x32x16_bf16 v[48:63], v[120:123], v[158:161], v[32:47]
	v_cvt_pk_bf16_f32 v144, v100, v101
	v_cvt_pk_bf16_f32 v145, v102, v103
	ds_read_b64_tr_b16 v[100:101], v189 offset:33792
	ds_read_b64_tr_b16 v[102:103], v189 offset:34304
	v_add_f32_e32 v120, v106, v129
	v_add_f32_e32 v120, v107, v120
	v_add_f32_e32 v120, v108, v120
	v_add_f32_e32 v120, v109, v120
	v_cvt_pk_bf16_f32 v138, v104, v105
	v_cvt_pk_bf16_f32 v139, v106, v107
	s_waitcnt lgkmcnt(11)
	v_mfma_f32_32x32x16_bf16 v[80:95], v[124:127], v[154:157], v[80:95]
	ds_read_b64_tr_b16 v[104:105], v189 offset:37888
	ds_read_b64_tr_b16 v[106:107], v189 offset:38400
	s_waitcnt lgkmcnt(12)
	v_mfma_f32_32x32x16_bf16 v[48:63], v[162:165], v[154:157], v[48:63]
	v_add_f32_e32 v120, v110, v120
	v_add_f32_e32 v120, v111, v120
	v_add_f32_e32 v120, v64, v120
	v_add_f32_e32 v124, v65, v120
	v_cvt_pk_bf16_f32 v140, v108, v109
	v_cvt_pk_bf16_f32 v141, v110, v111
	ds_read_b64_tr_b16 v[120:121], v189 offset:34816
	ds_read_b64_tr_b16 v[122:123], v189 offset:35328
	v_add_f32_e32 v108, v66, v124
	v_add_f32_e32 v108, v67, v108
	v_add_f32_e32 v108, v68, v108
	v_add_f32_e32 v108, v69, v108
	v_cvt_pk_bf16_f32 v134, v64, v65
	v_cvt_pk_bf16_f32 v135, v66, v67
	s_waitcnt lgkmcnt(13)
	v_mfma_f32_32x32x16_bf16 v[80:95], v[166:169], v[150:153], v[80:95]
	ds_read_b64_tr_b16 v[64:65], v189 offset:38912
	ds_read_b64_tr_b16 v[66:67], v189 offset:39424
	s_waitcnt lgkmcnt(14)
	v_mfma_f32_32x32x16_bf16 v[48:63], v[170:173], v[150:153], v[48:63]
	v_add_f32_e32 v108, v70, v108
	v_add_f32_e32 v108, v71, v108
	v_add_f32_e32 v108, v72, v108
	v_add_f32_e32 v108, v73, v108
	v_cvt_pk_bf16_f32 v136, v68, v69
	v_cvt_pk_bf16_f32 v137, v70, v71
	ds_read_b64_tr_b16 v[68:69], v189 offset:35840
	ds_read_b64_tr_b16 v[70:71], v189 offset:36352
	v_add_f32_e32 v108, v74, v108
	v_add_f32_e32 v108, v75, v108
	v_add_f32_e32 v108, v76, v108
	v_add_f32_e32 v108, v77, v108
	v_cvt_pk_bf16_f32 v130, v72, v73
	v_cvt_pk_bf16_f32 v131, v74, v75
	s_waitcnt lgkmcnt(14)
	v_mfma_f32_32x32x16_bf16 v[80:95], v[116:119], v[146:149], v[80:95]
	ds_read_b64_tr_b16 v[72:73], v189 offset:39936
	ds_read_b64_tr_b16 v[74:75], v189 offset:40448
	v_mfma_f32_32x32x16_bf16 v[48:63], v[112:115], v[146:149], v[48:63]
	v_add_f32_e32 v108, v78, v108
	v_add_f32_e32 v108, v79, v108
	v_add_f32_e32 v108, 0, v108
	v_cvt_pk_bf16_f32 v132, v76, v77
	v_cvt_pk_bf16_f32 v133, v78, v79
	s_add_u32 s8, s8, 0xbd0000
	s_addc_u32 s9, s9, 0
	s_mov_b32 s10, m0
	s_mov_b32 m0, s15
	s_nop 0
	global_load_lds_dwordx4 v185, s[8:9]
	s_mov_b32 m0, s10
	v_add_f32_e32 v108, v128, v108
	s_waitcnt lgkmcnt(14)
	v_mfma_f32_32x32x16_bf16 v[0:15], v[142:145], v[174:177], v[0:15]
	v_exp_f32_e32 v80, v80
	v_exp_f32_e32 v81, v81
	v_exp_f32_e32 v82, v82
	v_exp_f32_e32 v83, v83
	s_waitcnt lgkmcnt(12)
	v_mfma_f32_32x32x16_bf16 v[16:31], v[142:145], v[96:99], v[16:31]
	v_exp_f32_e32 v84, v84
	v_exp_f32_e32 v85, v85
	v_exp_f32_e32 v86, v86
	v_exp_f32_e32 v87, v87
	ds_read_b128 v[110:113], v187
	ds_read_b128 v[114:117], v187 offset:512
	s_waitcnt lgkmcnt(12)
	v_mfma_f32_32x32x16_bf16 v[0:15], v[138:141], v[100:103], v[0:15]
	v_exp_f32_e32 v88, v88
	v_exp_f32_e32 v89, v89
	v_exp_f32_e32 v90, v90
	v_exp_f32_e32 v91, v91
	ds_read_b128 v[124:127], v187 offset:2048
	ds_read_b128 v[162:165], v187 offset:2560
	s_waitcnt lgkmcnt(12)
	v_mfma_f32_32x32x16_bf16 v[16:31], v[138:141], v[104:107], v[16:31]
	v_exp_f32_e32 v92, v92
	v_exp_f32_e32 v93, v93
	v_exp_f32_e32 v94, v94
	v_exp_f32_e32 v95, v95
	ds_read_b128 v[166:169], v187 offset:4096
	ds_read_b128 v[170:173], v187 offset:4608
	s_waitcnt lgkmcnt(12)
	v_mfma_f32_32x32x16_bf16 v[0:15], v[134:137], v[120:123], v[0:15]
	v_exp_f32_e32 v48, v48
	v_exp_f32_e32 v49, v49
	v_exp_f32_e32 v50, v50
	v_exp_f32_e32 v51, v51
	ds_read_b128 v[118:121], v187 offset:6144
	ds_read_b128 v[104:107], v187 offset:6656
	s_waitcnt lgkmcnt(12)
	v_mfma_f32_32x32x16_bf16 v[16:31], v[134:137], v[64:67], v[16:31]
	v_exp_f32_e32 v52, v52
	v_exp_f32_e32 v53, v53
	v_exp_f32_e32 v54, v54
	v_exp_f32_e32 v55, v55
	s_waitcnt lgkmcnt(10)
	v_mfma_f32_32x32x16_bf16 v[0:15], v[130:133], v[68:71], v[0:15]
	v_exp_f32_e32 v56, v56
	v_exp_f32_e32 v57, v57
	v_exp_f32_e32 v58, v58
	v_exp_f32_e32 v59, v59
	s_waitcnt lgkmcnt(8)
	v_mfma_f32_32x32x16_bf16 v[16:31], v[130:133], v[72:75], v[16:31]
	v_exp_f32_e32 v60, v60
	v_exp_f32_e32 v61, v61
	v_exp_f32_e32 v62, v62
	v_exp_f32_e32 v63, v63
	s_waitcnt vmcnt(0) lgkmcnt(0)
	s_barrier
	ds_read_b64_tr_b16 v[96:97], v189 offset:40960
	ds_read_b64_tr_b16 v[98:99], v189 offset:41472
	v_add_f32_e32 v64, v80, v81
	v_add_f32_e32 v64, v82, v64
	v_add_f32_e32 v64, v83, v64
	v_add_f32_e32 v64, v84, v64
	v_add_f32_e32 v100, v85, v64
	v_cvt_pk_bf16_f32 v142, v80, v81
	v_cvt_pk_bf16_f32 v143, v82, v83
	s_waitcnt lgkmcnt(9)
	v_mfma_f32_32x32x16_bf16 v[64:79], v[110:113], v[158:161], v[32:47]
	ds_read_b64_tr_b16 v[80:81], v189 offset:45056
	ds_read_b64_tr_b16 v[82:83], v189 offset:45568
	s_waitcnt lgkmcnt(10)
	v_mfma_f32_32x32x16_bf16 v[32:47], v[114:117], v[158:161], v[32:47]
	v_add_f32_e32 v100, v86, v100
	v_add_f32_e32 v100, v87, v100
	v_add_f32_e32 v100, v88, v100
	v_add_f32_e32 v109, v89, v100
	v_cvt_pk_bf16_f32 v144, v84, v85
	v_cvt_pk_bf16_f32 v145, v86, v87
	ds_read_b64_tr_b16 v[100:101], v189 offset:41984
	ds_read_b64_tr_b16 v[102:103], v189 offset:42496
	v_add_f32_e32 v84, v90, v109
	v_add_f32_e32 v84, v91, v84
	v_add_f32_e32 v84, v92, v84
	v_add_f32_e32 v109, v93, v84
	v_cvt_pk_bf16_f32 v138, v88, v89
	v_cvt_pk_bf16_f32 v139, v90, v91
	s_waitcnt lgkmcnt(11)
	v_mfma_f32_32x32x16_bf16 v[64:79], v[124:127], v[154:157], v[64:79]
	ds_read_b64_tr_b16 v[84:85], v189 offset:46080
	ds_read_b64_tr_b16 v[86:87], v189 offset:46592
	s_waitcnt lgkmcnt(12)
	v_mfma_f32_32x32x16_bf16 v[32:47], v[162:165], v[154:157], v[32:47]
	v_add_f32_e32 v88, v94, v109
	v_add_f32_e32 v88, v95, v88
	v_add_f32_e32 v88, v48, v88
	v_add_f32_e32 v109, v49, v88
	v_cvt_pk_bf16_f32 v140, v92, v93
	v_cvt_pk_bf16_f32 v141, v94, v95
	ds_read_b64_tr_b16 v[88:89], v189 offset:43008
	ds_read_b64_tr_b16 v[90:91], v189 offset:43520
	v_add_f32_e32 v92, v50, v109
	v_add_f32_e32 v92, v51, v92
	v_add_f32_e32 v92, v52, v92
	v_add_f32_e32 v92, v53, v92
	v_cvt_pk_bf16_f32 v134, v48, v49
	v_cvt_pk_bf16_f32 v135, v50, v51
	s_waitcnt lgkmcnt(13)
	v_mfma_f32_32x32x16_bf16 v[64:79], v[166:169], v[150:153], v[64:79]
	ds_read_b64_tr_b16 v[48:49], v189 offset:47104
	ds_read_b64_tr_b16 v[50:51], v189 offset:47616
	s_waitcnt lgkmcnt(14)
	v_mfma_f32_32x32x16_bf16 v[32:47], v[170:173], v[150:153], v[32:47]
	v_add_f32_e32 v92, v54, v92
	v_add_f32_e32 v92, v55, v92
	v_add_f32_e32 v92, v56, v92
	v_add_f32_e32 v109, v57, v92
	v_cvt_pk_bf16_f32 v136, v52, v53
	v_cvt_pk_bf16_f32 v137, v54, v55
	ds_read_b64_tr_b16 v[92:93], v189 offset:44032
	ds_read_b64_tr_b16 v[94:95], v189 offset:44544
	v_add_f32_e32 v52, v58, v109
	v_add_f32_e32 v52, v59, v52
	v_add_f32_e32 v52, v60, v52
	v_add_f32_e32 v109, v61, v52
	v_cvt_pk_bf16_f32 v130, v56, v57
	v_cvt_pk_bf16_f32 v131, v58, v59
	s_waitcnt lgkmcnt(14)
	v_mfma_f32_32x32x16_bf16 v[64:79], v[118:121], v[146:149], v[64:79]
	ds_read_b64_tr_b16 v[52:53], v189 offset:48128
	ds_read_b64_tr_b16 v[54:55], v189 offset:48640
	v_mfma_f32_32x32x16_bf16 v[32:47], v[104:107], v[146:149], v[32:47]
	v_add_f32_e32 v56, v62, v109
	v_add_f32_e32 v56, v63, v56
	v_add_f32_e32 v56, 0, v56
	v_cvt_pk_bf16_f32 v132, v60, v61
	v_cvt_pk_bf16_f32 v133, v62, v63
	s_nop 3
	v_exp_f32_e32 v64, v64
	v_exp_f32_e32 v65, v65
	v_exp_f32_e32 v66, v66
	v_exp_f32_e32 v67, v67
	s_nop 0
	v_exp_f32_e32 v68, v68
	v_exp_f32_e32 v69, v69
	v_exp_f32_e32 v70, v70
	v_exp_f32_e32 v71, v71
	s_nop 0
	v_exp_f32_e32 v72, v72
	v_exp_f32_e32 v73, v73
	v_exp_f32_e32 v74, v74
	v_exp_f32_e32 v75, v75
	s_nop 0
	v_exp_f32_e32 v76, v76
	v_exp_f32_e32 v77, v77
	v_exp_f32_e32 v78, v78
	v_exp_f32_e32 v79, v79
	v_exp_f32_e32 v32, v32
	v_exp_f32_e32 v33, v33
	v_exp_f32_e32 v34, v34
	v_exp_f32_e32 v35, v35
	s_nop 0
	v_exp_f32_e32 v36, v36
	v_exp_f32_e32 v37, v37
	v_exp_f32_e32 v38, v38
	v_exp_f32_e32 v39, v39
	s_nop 0
	v_exp_f32_e32 v40, v40
	v_exp_f32_e32 v41, v41
	v_exp_f32_e32 v42, v42
	v_exp_f32_e32 v43, v43
	s_nop 0
	v_exp_f32_e32 v44, v44
	v_exp_f32_e32 v45, v45
	v_exp_f32_e32 v46, v46
	v_exp_f32_e32 v47, v47
	s_waitcnt lgkmcnt(14)
; #define SBAR() __builtin_amdgcn_sched_barrier(0)
;   #define RESC() do { if constexpr (!NOMAX) if (resc) { asm volatile("s_waitcnt lgkmcnt(0)" ::: "memory"); \
;       _Pragma("unroll") for (int d_ = 0; d_ < 2 * DV2; ++d_) _Pragma("unroll") for (int r = 0; r < 16; ++r) o[d_][r] *= wsf[crow(r, hi)]; } } while (0)
;   #define PKW(P, B) cvtpk_s(P[B], P[B + 1])
;     ...
;   STEP(pB0, pB1, pA0, pA1, NT - 1, false, false, false); RESC();
;   { float sacc = pB0[0] + pB0[1]; _Pragma("unroll") for (int r = 2; r < 16; ++r) sacc += pB0[r]; _Pragma("unroll") for (int r = 0; r < 16; ++r) sacc += pB1[r]; l_reg += sacc;
;     pw0 = (u32x4){PKW(pB0, 0), PKW(pB0, 2), PKW(pB0, 4), PKW(pB0, 6)}; pw1 = (u32x4){PKW(pB0, 8), PKW(pB0, 10), PKW(pB0, 12), PKW(pB0, 14)}; pw2 = (u32x4){PKW(pB1, 0), PKW(pB1, 2), PKW(pB1, 4), PKW(pB1, 6)}; pw3 = (u32x4){PKW(pB1, 8), PKW(pB1, 10), PKW(pB1, 12), PKW(pB1, 14)};
;     SBAR(); pv(o, vb0 + DV2 * sl_cur, PAF(0), PAF(1), PAF(2), PAF(3)); if constexpr (DV2 == 2) pv(o + 2, vb0 + DV2 * sl_cur + 8192, PAF(0), PAF(1), PAF(2), PAF(3)); }
;     ...
;   { auto rr = __builtin_amdgcn_permlane32_swap(__float_as_uint(l_reg), __float_as_uint(l_reg), false, false); l_reg = __uint_as_float(rr[0]) + __uint_as_float(rr[1]); }
;   int lane_e; asm volatile("v_mbcnt_lo_u32_b32 %0, -1, 0\n\tv_mbcnt_hi_u32_b32 %0, -1, %0" : "=v"(lane_e));
;   const int r32e = lane_e & 31, hie = lane_e >> 5;
;   if (hie == 0) wsf[32 + r32e] = l_reg; asm volatile("s_waitcnt lgkmcnt(0)" ::: "memory");
	v_mfma_f32_32x32x16_bf16 v[0:15], v[142:145], v[96:99], v[0:15]
	v_add_f32_e32 v57, v64, v65
	v_add_f32_e32 v57, v66, v57
	v_add_f32_e32 v57, v67, v57
	v_add_f32_e32 v57, v68, v57
	v_add_f32_e32 v57, v69, v57
	v_add_f32_e32 v57, v70, v57
	v_add_f32_e32 v57, v71, v57
	s_waitcnt lgkmcnt(12)
	v_mfma_f32_32x32x16_bf16 v[16:31], v[142:145], v[80:83], v[16:31]
	v_add_f32_e32 v57, v72, v57
	v_add_f32_e32 v57, v73, v57
	v_add_f32_e32 v57, v74, v57
	v_add_f32_e32 v57, v75, v57
	v_add_f32_e32 v57, v76, v57
	v_add_f32_e32 v57, v77, v57
	v_add_f32_e32 v57, v78, v57
	s_waitcnt lgkmcnt(10)
	v_mfma_f32_32x32x16_bf16 v[0:15], v[138:141], v[100:103], v[0:15]
	v_add_f32_e32 v57, v79, v57
	v_add_f32_e32 v57, v32, v57
	v_add_f32_e32 v57, v33, v57
	v_add_f32_e32 v57, v34, v57
	v_add_f32_e32 v57, v35, v57
	v_add_f32_e32 v57, v36, v57
	v_add_f32_e32 v57, v37, v57
	s_waitcnt lgkmcnt(8)
	v_mfma_f32_32x32x16_bf16 v[16:31], v[138:141], v[84:87], v[16:31]
	v_add_f32_e32 v57, v38, v57
	v_add_f32_e32 v57, v39, v57
	v_add_f32_e32 v57, v40, v57
	v_add_f32_e32 v57, v41, v57
	v_add_f32_e32 v57, v42, v57
	v_add_f32_e32 v57, v43, v57
	v_add_f32_e32 v57, v44, v57
	s_waitcnt lgkmcnt(6)
	v_mfma_f32_32x32x16_bf16 v[0:15], v[134:137], v[88:91], v[0:15]
	v_add_f32_e32 v57, v45, v57
	v_add_f32_e32 v57, v46, v57
	v_add_f32_e32 v57, v47, v57
	v_add_f32_e32 v56, v108, v56
	v_add_f32_e32 v56, v56, v57
	v_cvt_pk_bf16_f32 v32, v32, v33
	v_cvt_pk_bf16_f32 v33, v34, v35
	s_waitcnt lgkmcnt(4)
	v_mfma_f32_32x32x16_bf16 v[16:31], v[134:137], v[48:51], v[16:31]
	v_cvt_pk_bf16_f32 v58, v64, v65
	v_cvt_pk_bf16_f32 v59, v66, v67
	v_cvt_pk_bf16_f32 v60, v68, v69
	v_cvt_pk_bf16_f32 v61, v70, v71
	v_cvt_pk_bf16_f32 v62, v72, v73
	v_cvt_pk_bf16_f32 v63, v74, v75
	v_cvt_pk_bf16_f32 v64, v76, v77
	s_waitcnt lgkmcnt(2)
	v_mfma_f32_32x32x16_bf16 v[0:15], v[130:133], v[92:95], v[0:15]
	v_cvt_pk_bf16_f32 v65, v78, v79
	v_cvt_pk_bf16_f32 v34, v36, v37
	v_cvt_pk_bf16_f32 v35, v38, v39
	v_cvt_pk_bf16_f32 v36, v40, v41
	v_cvt_pk_bf16_f32 v37, v42, v43
	v_cvt_pk_bf16_f32 v38, v44, v45
	v_cvt_pk_bf16_f32 v39, v46, v47
	s_waitcnt lgkmcnt(0)
	v_mfma_f32_32x32x16_bf16 v[16:31], v[130:133], v[52:55], v[16:31]
	ds_read_b64_tr_b16 v[40:41],v188 offset:0
	ds_read_b64_tr_b16 v[42:43],v188 offset:512
	ds_read_b64_tr_b16 v[44:45],v188 offset:1024
	ds_read_b64_tr_b16 v[46:47],v188 offset:1536
	ds_read_b64_tr_b16 v[48:49],v188 offset:2048
	ds_read_b64_tr_b16 v[50:51],v188 offset:2560
	ds_read_b64_tr_b16 v[52:53],v188 offset:3072
	ds_read_b64_tr_b16 v[54:55],v188 offset:3584
	s_waitcnt lgkmcnt(0)
	s_nop 0
	v_mfma_f32_32x32x16_bf16 v[0:15], v[58:61], v[40:43], v[0:15]
	ds_read_b64_tr_b16 v[40:41],v188 offset:4096
	ds_read_b64_tr_b16 v[42:43],v188 offset:4608
	v_mfma_f32_32x32x16_bf16 v[0:15], v[62:65], v[44:47], v[0:15]
	ds_read_b64_tr_b16 v[44:45],v188 offset:5120
	ds_read_b64_tr_b16 v[46:47],v188 offset:5632
	v_mfma_f32_32x32x16_bf16 v[0:15], v[32:35], v[48:51], v[0:15]
	ds_read_b64_tr_b16 v[48:49],v188 offset:6144
	ds_read_b64_tr_b16 v[50:51],v188 offset:6656
	v_mfma_f32_32x32x16_bf16 v[0:15], v[36:39], v[52:55], v[0:15]
	ds_read_b64_tr_b16 v[52:53],v188 offset:7168
	ds_read_b64_tr_b16 v[54:55],v188 offset:7680
	s_waitcnt lgkmcnt(0)
	v_mfma_f32_32x32x16_bf16 v[16:31], v[58:61], v[40:43], v[16:31]
	v_mfma_f32_32x32x16_bf16 v[16:31], v[62:65], v[44:47], v[16:31]
	v_mfma_f32_32x32x16_bf16 v[16:31], v[32:35], v[48:51], v[16:31]
	v_mov_b32_e32 v33, v56
	s_nop 1
	v_permlane32_swap_b32_e32 v56, v33
	v_mbcnt_lo_u32_b32 v32, -1, 0
	v_mbcnt_hi_u32_b32 v32, -1, v32
	s_nop 0
	v_cmp_gt_u32_e32 vcc, 32, v32
	v_mfma_f32_32x32x16_bf16 v[16:31], v[36:39], v[52:55], v[16:31]
	s_and_saveexec_b64 s[8:9], vcc
	s_cbranch_execz .LBB0_968
	v_add_f32_e32 v33, v56, v33
	v_lshl_add_u32 v34, v32, 2, s16
	ds_write_b32 v34, v33 offset:49280
	s_branch .LBB0_968
